# P5 key-value expansion epilogue: rotated-key rows loaded once up front by the copying waves instead of 16 load-wait-store round trips
# speedup vs baseline: 1.0181x; 1.0038x over previous
.LBB0_732:
	s_lshl_b32 s35, s42, 8
	s_add_i32 s35, s35, s54
	v_or_b32_e32 v144, s35, v1
	v_ashrrev_i32_e32 v145, 31, v144
	v_lshlrev_b64 v[146:147], 5, v[144:145]
	v_lshl_add_u64 v[146:147], s[10:11], 0, v[146:147]
	global_load_dwordx4 v[158:161], v[146:147], off offset:16
	s_lshl_b32 s42, s6, 1
	s_ashr_i32 s44, s35, 13
	s_ashr_i32 s43, s42, 31
	s_ashr_i32 s45, s44, 31
	v_mad_i64_i32 v[146:147], s[46:47], v144, s60, 0
	v_cndmask_b32_e64 v145, 0, 1, s[28:29]
	s_lshl_b64 s[42:43], s[42:43], 13
	s_lshl_b64 s[46:47], s[44:45], 16
	v_cmp_ne_u32_e64 s[6:7], 1, v145
	v_bitop3_b32 v145, s35, v156, v1 bitop3:0xc8
	s_add_u32 s45, s46, s42
	v_mov_b64_e32 v[148:149], s[14:15]
	v_or_b32_e32 v150, s45, v145
	s_addc_u32 s44, s47, s43
	v_mad_u64_u32 v[150:151], s[46:47], v150, s60, v[148:149]
	v_mad_i32_i24 v151, s44, v157, v151
	s_and_b64 vcc, exec, s[6:7]
	s_cbranch_vccnz .Lkv_nopref
	v_lshl_add_u64 v[238:239], v[138:139], 0, v[146:147]
	global_load_dwordx4 v[206:209], v[238:239], off offset:256
	v_add_co_u32_e32 v240, vcc, 0x1400, v238
	s_nop 1
	v_addc_co_u32_e32 v241, vcc, 0, v239, vcc
	global_load_dwordx4 v[210:213], v[240:241], off offset:256
	v_add_co_u32_e32 v240, vcc, 0x2800, v238
	s_nop 1
	v_addc_co_u32_e32 v241, vcc, 0, v239, vcc
	global_load_dwordx4 v[214:217], v[240:241], off offset:256
	v_add_co_u32_e32 v240, vcc, 0x3c00, v238
	s_nop 1
	v_addc_co_u32_e32 v241, vcc, 0, v239, vcc
	global_load_dwordx4 v[218:221], v[240:241], off offset:256
	v_add_co_u32_e32 v240, vcc, 0xa000, v238
	s_nop 1
	v_addc_co_u32_e32 v241, vcc, 0, v239, vcc
	global_load_dwordx4 v[222:225], v[240:241], off offset:256
	v_add_co_u32_e32 v240, vcc, 0xb400, v238
	s_nop 1
	v_addc_co_u32_e32 v241, vcc, 0, v239, vcc
	global_load_dwordx4 v[226:229], v[240:241], off offset:256
	v_add_co_u32_e32 v240, vcc, 0xc800, v238
	s_nop 1
	v_addc_co_u32_e32 v241, vcc, 0, v239, vcc
	global_load_dwordx4 v[230:233], v[240:241], off offset:256
	v_add_co_u32_e32 v240, vcc, 0xdc00, v238
	s_nop 1
	v_addc_co_u32_e32 v241, vcc, 0, v239, vcc
	global_load_dwordx4 v[234:237], v[240:241], off offset:256
.Lkv_nopref:
	s_andn2_b64 vcc, exec, s[28:29]
	s_waitcnt vmcnt(0)
	v_mov_b32_e32 v148, v159
	v_mov_b32_e32 v149, v160
	v_mov_b32_e32 v159, v161
	v_pk_add_f32 v[148:149], v[148:149], v[158:159]
	v_lshl_add_u64 v[158:159], v[150:151], 0, s[8:9]
	v_add_f32_e32 v148, v148, v149
	v_fmamk_f32 v148, v148, 0x3c000000, v155
	v_rsq_f32_e32 v148, v148
	v_lshl_add_u64 v[158:159], v[158:159], 0, v[134:135]
	v_pk_mul_f32 v[122:123], v[122:123], v[148:149] op_sel_hi:[1,0]
	v_pk_mul_f32 v[124:125], v[124:125], v[148:149] op_sel_hi:[1,0]
	v_cvt_pk_bf16_f32 v122, v122, v123
	v_pk_mul_f32 v[128:129], v[128:129], v[148:149] op_sel_hi:[1,0]
	v_cvt_pk_bf16_f32 v123, v124, v125
	v_pk_mul_f32 v[126:127], v[126:127], v[148:149] op_sel_hi:[1,0]
	global_store_dwordx2 v[158:159], v[122:123], off
	v_cvt_pk_bf16_f32 v122, v126, v127
	v_cvt_pk_bf16_f32 v123, v128, v129
	global_store_dwordx2 v[158:159], v[122:123], off offset:32
	s_cbranch_vccnz .LBB0_734
	v_lshlrev_b32_e32 v126, 1, v136
	v_mov_b32_e32 v127, v135
	v_lshl_add_u64 v[126:127], v[150:151], 0, v[126:127]
	global_store_dwordx4 v[126:127], v[206:209], off offset:256
.LBB0_734:
	s_or_b32 s37, s45, 0x2000
	s_nop 0
	v_or_b32_e32 v124, s37, v145
	v_mov_b64_e32 v[122:123], s[14:15]
	v_mad_u64_u32 v[122:123], s[46:47], v124, s60, v[122:123]
	v_mad_i32_i24 v123, s44, v157, v123
	v_mov_b32_e32 v149, v148
	v_lshl_add_u64 v[124:125], v[122:123], 0, s[8:9]
	v_lshl_add_u64 v[124:125], v[124:125], 0, v[134:135]
	v_mov_b32_e32 v126, v148
	v_mov_b32_e32 v127, v148
	v_pk_mul_f32 v[118:119], v[118:119], v[148:149]
	v_pk_mul_f32 v[114:115], v[114:115], v[148:149]
	s_and_b64 vcc, exec, s[6:7]
	v_pk_mul_f32 v[120:121], v[120:121], v[126:127]
	v_cvt_pk_bf16_f32 v118, v118, v119
	v_pk_mul_f32 v[116:117], v[116:117], v[126:127]
	v_cvt_pk_bf16_f32 v119, v120, v121
	global_store_dwordx2 v[124:125], v[118:119], off
	v_cvt_pk_bf16_f32 v114, v114, v115
	v_cvt_pk_bf16_f32 v115, v116, v117
	global_store_dwordx2 v[124:125], v[114:115], off offset:32
	s_cbranch_vccnz .LBB0_736
	v_lshlrev_b32_e32 v118, 1, v136
	v_mov_b32_e32 v119, v135
	v_lshl_add_u64 v[118:119], v[122:123], 0, v[118:119]
	global_store_dwordx4 v[118:119], v[206:209], off offset:256
.LBB0_736:
	s_nop 1
	v_or_b32_e32 v114, 16, v144
	v_ashrrev_i32_e32 v115, 31, v114
	v_lshlrev_b64 v[116:117], 5, v[114:115]
	v_lshl_add_u64 v[116:117], s[10:11], 0, v[116:117]
	global_load_dwordx4 v[122:125], v[116:117], off offset:16
	v_bitop3_b32 v120, v144, s61, 16 bitop3:0xc8
	v_mov_b64_e32 v[116:117], s[14:15]
	v_or_b32_e32 v118, s45, v120
	v_mad_u64_u32 v[118:119], s[46:47], v118, s60, v[116:117]
	v_mad_i32_i24 v119, s44, v157, v119
	v_mad_i64_i32 v[114:115], s[46:47], v114, s60, 0
	s_and_b64 vcc, exec, s[6:7]
	s_waitcnt vmcnt(0)
	v_mov_b32_e32 v116, v123
	v_mov_b32_e32 v117, v124
	v_mov_b32_e32 v123, v125
	v_pk_add_f32 v[116:117], v[116:117], v[122:123]
	v_lshl_add_u64 v[122:123], v[118:119], 0, s[8:9]
	v_add_f32_e32 v116, v116, v117
	v_fmamk_f32 v116, v116, 0x3c000000, v155
	v_rsq_f32_e32 v116, v116
	v_lshl_add_u64 v[122:123], v[122:123], 0, v[134:135]
	v_pk_mul_f32 v[110:111], v[110:111], v[116:117] op_sel_hi:[1,0]
	v_pk_mul_f32 v[106:107], v[106:107], v[116:117] op_sel_hi:[1,0]
	v_pk_mul_f32 v[112:113], v[112:113], v[116:117] op_sel_hi:[1,0]
	v_pk_mul_f32 v[108:109], v[108:109], v[116:117] op_sel_hi:[1,0]
	v_cvt_pk_bf16_f32 v110, v110, v111
	v_cvt_pk_bf16_f32 v111, v112, v113
	global_store_dwordx2 v[122:123], v[110:111], off
	v_cvt_pk_bf16_f32 v106, v106, v107
	v_cvt_pk_bf16_f32 v107, v108, v109
	global_store_dwordx2 v[122:123], v[106:107], off offset:32
	s_cbranch_vccnz .LBB0_738
	v_lshlrev_b32_e32 v110, 1, v136
	v_mov_b32_e32 v111, v135
	v_lshl_add_u64 v[110:111], v[118:119], 0, v[110:111]
	global_store_dwordx4 v[110:111], v[210:213], off offset:256
.LBB0_738:
	s_nop 1
	v_or_b32_e32 v108, s37, v120
	v_mov_b64_e32 v[106:107], s[14:15]
	s_mul_i32 s46, s44, 0x140
	v_mad_u64_u32 v[106:107], s[48:49], v108, s60, v[106:107]
	v_add_u32_e32 v107, s46, v107
	v_mov_b32_e32 v117, v116
	v_lshl_add_u64 v[108:109], v[106:107], 0, s[8:9]
	v_lshl_add_u64 v[108:109], v[108:109], 0, v[134:135]
	v_mov_b32_e32 v110, v116
	v_mov_b32_e32 v111, v116
	v_pk_mul_f32 v[102:103], v[102:103], v[116:117]
	v_pk_mul_f32 v[98:99], v[98:99], v[116:117]
	s_and_b64 vcc, exec, s[6:7]
	v_pk_mul_f32 v[104:105], v[104:105], v[110:111]
	v_cvt_pk_bf16_f32 v102, v102, v103
	v_pk_mul_f32 v[100:101], v[100:101], v[110:111]
	v_cvt_pk_bf16_f32 v103, v104, v105
	global_store_dwordx2 v[108:109], v[102:103], off
	v_cvt_pk_bf16_f32 v98, v98, v99
	v_cvt_pk_bf16_f32 v99, v100, v101
	global_store_dwordx2 v[108:109], v[98:99], off offset:32
	s_cbranch_vccnz .LBB0_740
	v_lshlrev_b32_e32 v102, 1, v136
	v_mov_b32_e32 v103, v135
	v_lshl_add_u64 v[102:103], v[106:107], 0, v[102:103]
	global_store_dwordx4 v[102:103], v[210:213], off offset:256
.LBB0_740:
	s_nop 1
	v_or_b32_e32 v98, 32, v144
	v_ashrrev_i32_e32 v99, 31, v98
	v_lshlrev_b64 v[100:101], 5, v[98:99]
	v_lshl_add_u64 v[100:101], s[10:11], 0, v[100:101]
	global_load_dwordx4 v[106:109], v[100:101], off offset:16
	v_bitop3_b32 v104, v144, s64, 32 bitop3:0xc8
	v_mov_b64_e32 v[100:101], s[14:15]
	v_or_b32_e32 v102, s45, v104
	v_mad_u64_u32 v[102:103], s[48:49], v102, s60, v[100:101]
	v_mad_i32_i24 v103, s44, v157, v103
	v_mad_i64_i32 v[98:99], s[48:49], v98, s60, 0
	s_and_b64 vcc, exec, s[6:7]
	s_waitcnt vmcnt(0)
	v_mov_b32_e32 v100, v107
	v_mov_b32_e32 v101, v108
	v_mov_b32_e32 v107, v109
	v_pk_add_f32 v[100:101], v[100:101], v[106:107]
	v_lshl_add_u64 v[106:107], v[102:103], 0, s[8:9]
	v_add_f32_e32 v100, v100, v101
	v_fmamk_f32 v100, v100, 0x3c000000, v155
	v_rsq_f32_e32 v100, v100
	v_lshl_add_u64 v[106:107], v[106:107], 0, v[134:135]
	v_pk_mul_f32 v[94:95], v[94:95], v[100:101] op_sel_hi:[1,0]
	v_pk_mul_f32 v[90:91], v[90:91], v[100:101] op_sel_hi:[1,0]
	v_pk_mul_f32 v[96:97], v[96:97], v[100:101] op_sel_hi:[1,0]
	v_pk_mul_f32 v[92:93], v[92:93], v[100:101] op_sel_hi:[1,0]
	v_cvt_pk_bf16_f32 v94, v94, v95
	v_cvt_pk_bf16_f32 v95, v96, v97
	global_store_dwordx2 v[106:107], v[94:95], off
	v_cvt_pk_bf16_f32 v90, v90, v91
	v_cvt_pk_bf16_f32 v91, v92, v93
	global_store_dwordx2 v[106:107], v[90:91], off offset:32
	s_cbranch_vccnz .LBB0_742
	v_lshlrev_b32_e32 v94, 1, v136
	v_mov_b32_e32 v95, v135
	v_lshl_add_u64 v[94:95], v[102:103], 0, v[94:95]
	global_store_dwordx4 v[94:95], v[214:217], off offset:256
.LBB0_742:
	s_nop 1
	v_or_b32_e32 v92, s37, v104
	v_mov_b64_e32 v[90:91], s[14:15]
	v_mad_u64_u32 v[90:91], s[48:49], v92, s60, v[90:91]
	v_add_u32_e32 v91, s46, v91
	v_mov_b32_e32 v101, v100
	v_lshl_add_u64 v[92:93], v[90:91], 0, s[8:9]
	v_lshl_add_u64 v[92:93], v[92:93], 0, v[134:135]
	v_mov_b32_e32 v94, v100
	v_mov_b32_e32 v95, v100
	v_pk_mul_f32 v[86:87], v[86:87], v[100:101]
	v_pk_mul_f32 v[82:83], v[82:83], v[100:101]
	s_and_b64 vcc, exec, s[6:7]
	v_pk_mul_f32 v[88:89], v[88:89], v[94:95]
	v_cvt_pk_bf16_f32 v86, v86, v87
	v_pk_mul_f32 v[84:85], v[84:85], v[94:95]
	v_cvt_pk_bf16_f32 v87, v88, v89
	global_store_dwordx2 v[92:93], v[86:87], off
	v_cvt_pk_bf16_f32 v82, v82, v83
	v_cvt_pk_bf16_f32 v83, v84, v85
	global_store_dwordx2 v[92:93], v[82:83], off offset:32
	s_cbranch_vccnz .LBB0_744
	v_lshlrev_b32_e32 v86, 1, v136
	v_mov_b32_e32 v87, v135
	v_lshl_add_u64 v[86:87], v[90:91], 0, v[86:87]
	global_store_dwordx4 v[86:87], v[214:217], off offset:256
.LBB0_744:
	s_nop 1
	v_or_b32_e32 v82, 48, v144
	v_ashrrev_i32_e32 v83, 31, v82
	v_lshlrev_b64 v[84:85], 5, v[82:83]
	v_lshl_add_u64 v[84:85], s[10:11], 0, v[84:85]
	global_load_dwordx4 v[90:93], v[84:85], off offset:16
	v_bitop3_b32 v88, v144, s65, 48 bitop3:0xc8
	v_mov_b64_e32 v[84:85], s[14:15]
	v_or_b32_e32 v86, s45, v88
	v_mad_u64_u32 v[86:87], s[48:49], v86, s60, v[84:85]
	v_mad_i32_i24 v87, s44, v157, v87
	v_mad_i64_i32 v[82:83], s[48:49], v82, s60, 0
	s_and_b64 vcc, exec, s[6:7]
	s_waitcnt vmcnt(0)
	v_mov_b32_e32 v84, v91
	v_mov_b32_e32 v85, v92
	v_mov_b32_e32 v91, v93
	v_pk_add_f32 v[84:85], v[84:85], v[90:91]
	v_lshl_add_u64 v[90:91], v[86:87], 0, s[8:9]
	v_add_f32_e32 v84, v84, v85
	v_fmamk_f32 v84, v84, 0x3c000000, v155
	v_rsq_f32_e32 v84, v84
	v_lshl_add_u64 v[90:91], v[90:91], 0, v[134:135]
	v_pk_mul_f32 v[78:79], v[78:79], v[84:85] op_sel_hi:[1,0]
	v_pk_mul_f32 v[74:75], v[74:75], v[84:85] op_sel_hi:[1,0]
	v_pk_mul_f32 v[80:81], v[80:81], v[84:85] op_sel_hi:[1,0]
	v_pk_mul_f32 v[76:77], v[76:77], v[84:85] op_sel_hi:[1,0]
	v_cvt_pk_bf16_f32 v78, v78, v79
	v_cvt_pk_bf16_f32 v79, v80, v81
	global_store_dwordx2 v[90:91], v[78:79], off
	v_cvt_pk_bf16_f32 v74, v74, v75
	v_cvt_pk_bf16_f32 v75, v76, v77
	global_store_dwordx2 v[90:91], v[74:75], off offset:32
	s_cbranch_vccnz .LBB0_746
	v_lshlrev_b32_e32 v78, 1, v136
	v_mov_b32_e32 v79, v135
	v_lshl_add_u64 v[78:79], v[86:87], 0, v[78:79]
	global_store_dwordx4 v[78:79], v[218:221], off offset:256
.LBB0_746:
	s_nop 1
	v_or_b32_e32 v76, s37, v88
	v_mov_b64_e32 v[74:75], s[14:15]
	v_mad_u64_u32 v[74:75], s[44:45], v76, s60, v[74:75]
	v_add_u32_e32 v75, s46, v75
	v_mov_b32_e32 v85, v84
	v_lshl_add_u64 v[76:77], v[74:75], 0, s[8:9]
	v_lshl_add_u64 v[76:77], v[76:77], 0, v[134:135]
	v_mov_b32_e32 v78, v84
	v_mov_b32_e32 v79, v84
	v_pk_mul_f32 v[70:71], v[70:71], v[84:85]
	v_pk_mul_f32 v[66:67], v[66:67], v[84:85]
	s_and_b64 vcc, exec, s[6:7]
	v_pk_mul_f32 v[72:73], v[72:73], v[78:79]
	v_cvt_pk_bf16_f32 v70, v70, v71
	v_pk_mul_f32 v[68:69], v[68:69], v[78:79]
	v_cvt_pk_bf16_f32 v71, v72, v73
	global_store_dwordx2 v[76:77], v[70:71], off
	v_cvt_pk_bf16_f32 v66, v66, v67
	v_cvt_pk_bf16_f32 v67, v68, v69
	global_store_dwordx2 v[76:77], v[66:67], off offset:32
	s_cbranch_vccnz .LBB0_748
	v_lshlrev_b32_e32 v70, 1, v136
	v_mov_b32_e32 v71, v135
	v_lshl_add_u64 v[70:71], v[74:75], 0, v[70:71]
	global_store_dwordx4 v[70:71], v[218:221], off offset:256
.LBB0_748:
	s_addk_i32 s35, 0x80
	s_nop 0
	v_or_b32_e32 v66, s35, v1
	v_ashrrev_i32_e32 v67, 31, v66
	v_lshlrev_b64 v[68:69], 5, v[66:67]
	v_lshl_add_u64 v[68:69], s[10:11], 0, v[68:69]
	global_load_dwordx4 v[74:77], v[68:69], off offset:16
	s_ashr_i32 s44, s35, 13
	s_ashr_i32 s45, s44, 31
	s_lshl_b64 s[44:45], s[44:45], 16
	v_bitop3_b32 v67, s35, v156, v1 bitop3:0xc8
	s_add_u32 s37, s44, s42
	v_mov_b64_e32 v[70:71], s[14:15]
	v_or_b32_e32 v72, s37, v67
	s_addc_u32 s35, s45, s43
	v_mad_u64_u32 v[72:73], s[42:43], v72, s60, v[70:71]
	v_mad_i32_i24 v73, s35, v157, v73
	v_mad_i64_i32 v[68:69], s[46:47], v66, s60, 0
	s_and_b64 vcc, exec, s[6:7]
	s_waitcnt vmcnt(0)
	v_mov_b32_e32 v70, v75
	v_mov_b32_e32 v71, v76
	v_mov_b32_e32 v75, v77
	v_pk_add_f32 v[70:71], v[70:71], v[74:75]
	v_lshl_add_u64 v[74:75], v[72:73], 0, s[8:9]
	v_add_f32_e32 v70, v70, v71
	v_fmamk_f32 v70, v70, 0x3c000000, v155
	v_rsq_f32_e32 v70, v70
	v_lshl_add_u64 v[74:75], v[74:75], 0, v[134:135]
	v_pk_mul_f32 v[62:63], v[62:63], v[70:71] op_sel_hi:[1,0]
	v_pk_mul_f32 v[58:59], v[58:59], v[70:71] op_sel_hi:[1,0]
	v_pk_mul_f32 v[64:65], v[64:65], v[70:71] op_sel_hi:[1,0]
	v_pk_mul_f32 v[60:61], v[60:61], v[70:71] op_sel_hi:[1,0]
	v_cvt_pk_bf16_f32 v62, v62, v63
	v_cvt_pk_bf16_f32 v63, v64, v65
	global_store_dwordx2 v[74:75], v[62:63], off
	v_cvt_pk_bf16_f32 v58, v58, v59
	v_cvt_pk_bf16_f32 v59, v60, v61
	global_store_dwordx2 v[74:75], v[58:59], off offset:32
	s_cbranch_vccnz .LBB0_750
	v_lshlrev_b32_e32 v62, 1, v136
	v_mov_b32_e32 v63, v135
	v_lshl_add_u64 v[62:63], v[72:73], 0, v[62:63]
	global_store_dwordx4 v[62:63], v[222:225], off offset:256
.LBB0_750:
	s_or_b32 s42, s37, 0x2000
	s_nop 0
	v_or_b32_e32 v60, s42, v67
	v_mov_b64_e32 v[58:59], s[14:15]
	v_mad_u64_u32 v[58:59], s[44:45], v60, s60, v[58:59]
	v_mad_i32_i24 v59, s35, v157, v59
	v_mov_b32_e32 v71, v70
	v_lshl_add_u64 v[60:61], v[58:59], 0, s[8:9]
	v_lshl_add_u64 v[60:61], v[60:61], 0, v[134:135]
	v_mov_b32_e32 v62, v70
	v_mov_b32_e32 v63, v70
	v_pk_mul_f32 v[54:55], v[54:55], v[70:71]
	v_pk_mul_f32 v[50:51], v[50:51], v[70:71]
	s_and_b64 vcc, exec, s[6:7]
	v_pk_mul_f32 v[56:57], v[56:57], v[62:63]
	v_cvt_pk_bf16_f32 v54, v54, v55
	v_pk_mul_f32 v[52:53], v[52:53], v[62:63]
	v_cvt_pk_bf16_f32 v55, v56, v57
	global_store_dwordx2 v[60:61], v[54:55], off
	v_cvt_pk_bf16_f32 v50, v50, v51
	v_cvt_pk_bf16_f32 v51, v52, v53
	global_store_dwordx2 v[60:61], v[50:51], off offset:32
	s_cbranch_vccnz .LBB0_752
	v_lshlrev_b32_e32 v54, 1, v136
	v_mov_b32_e32 v55, v135
	v_lshl_add_u64 v[54:55], v[58:59], 0, v[54:55]
	global_store_dwordx4 v[54:55], v[222:225], off offset:256
.LBB0_752:
	s_nop 1
	v_or_b32_e32 v50, 16, v66
	v_ashrrev_i32_e32 v51, 31, v50
	v_lshlrev_b64 v[52:53], 5, v[50:51]
	v_lshl_add_u64 v[52:53], s[10:11], 0, v[52:53]
	global_load_dwordx4 v[58:61], v[52:53], off offset:16
	v_bitop3_b32 v56, v66, s61, 16 bitop3:0xc8
	v_mov_b64_e32 v[52:53], s[14:15]
	v_or_b32_e32 v54, s37, v56
	v_mad_u64_u32 v[54:55], s[44:45], v54, s60, v[52:53]
	v_mad_i32_i24 v55, s35, v157, v55
	v_mad_i64_i32 v[50:51], s[44:45], v50, s60, 0
	s_and_b64 vcc, exec, s[6:7]
	s_waitcnt vmcnt(0)
	v_mov_b32_e32 v52, v59
	v_mov_b32_e32 v53, v60
	v_mov_b32_e32 v59, v61
	v_pk_add_f32 v[52:53], v[52:53], v[58:59]
	v_lshl_add_u64 v[58:59], v[54:55], 0, s[8:9]
	v_add_f32_e32 v52, v52, v53
	v_fmamk_f32 v52, v52, 0x3c000000, v155
	v_rsq_f32_e32 v52, v52
	v_lshl_add_u64 v[58:59], v[58:59], 0, v[134:135]
	v_pk_mul_f32 v[46:47], v[46:47], v[52:53] op_sel_hi:[1,0]
	v_pk_mul_f32 v[42:43], v[42:43], v[52:53] op_sel_hi:[1,0]
	v_pk_mul_f32 v[48:49], v[48:49], v[52:53] op_sel_hi:[1,0]
	v_pk_mul_f32 v[44:45], v[44:45], v[52:53] op_sel_hi:[1,0]
	v_cvt_pk_bf16_f32 v46, v46, v47
	v_cvt_pk_bf16_f32 v47, v48, v49
	global_store_dwordx2 v[58:59], v[46:47], off
	v_cvt_pk_bf16_f32 v42, v42, v43
	v_cvt_pk_bf16_f32 v43, v44, v45
	global_store_dwordx2 v[58:59], v[42:43], off offset:32
	s_cbranch_vccnz .LBB0_754
	v_lshlrev_b32_e32 v46, 1, v136
	v_mov_b32_e32 v47, v135
	v_lshl_add_u64 v[46:47], v[54:55], 0, v[46:47]
	global_store_dwordx4 v[46:47], v[226:229], off offset:256
.LBB0_754:
	s_nop 1
	v_or_b32_e32 v44, s42, v56
	v_mov_b64_e32 v[42:43], s[14:15]
	s_mul_i32 s43, s35, 0x140
	v_mad_u64_u32 v[42:43], s[44:45], v44, s60, v[42:43]
	v_add_u32_e32 v43, s43, v43
	v_mov_b32_e32 v53, v52
	v_lshl_add_u64 v[44:45], v[42:43], 0, s[8:9]
	v_lshl_add_u64 v[44:45], v[44:45], 0, v[134:135]
	v_mov_b32_e32 v46, v52
	v_mov_b32_e32 v47, v52
	v_pk_mul_f32 v[38:39], v[38:39], v[52:53]
	v_pk_mul_f32 v[34:35], v[34:35], v[52:53]
	s_and_b64 vcc, exec, s[6:7]
	v_pk_mul_f32 v[40:41], v[40:41], v[46:47]
	v_cvt_pk_bf16_f32 v38, v38, v39
	v_pk_mul_f32 v[36:37], v[36:37], v[46:47]
	v_cvt_pk_bf16_f32 v39, v40, v41
	global_store_dwordx2 v[44:45], v[38:39], off
	v_cvt_pk_bf16_f32 v34, v34, v35
	v_cvt_pk_bf16_f32 v35, v36, v37
	global_store_dwordx2 v[44:45], v[34:35], off offset:32
	s_cbranch_vccnz .LBB0_756
	v_lshlrev_b32_e32 v38, 1, v136
	v_mov_b32_e32 v39, v135
	v_lshl_add_u64 v[38:39], v[42:43], 0, v[38:39]
	global_store_dwordx4 v[38:39], v[226:229], off offset:256
.LBB0_756:
	s_nop 1
	v_or_b32_e32 v34, 32, v66
	v_ashrrev_i32_e32 v35, 31, v34
	v_lshlrev_b64 v[36:37], 5, v[34:35]
	v_lshl_add_u64 v[36:37], s[10:11], 0, v[36:37]
	global_load_dwordx4 v[42:45], v[36:37], off offset:16
	v_bitop3_b32 v40, v66, s64, 32 bitop3:0xc8
	v_mov_b64_e32 v[36:37], s[14:15]
	v_or_b32_e32 v38, s37, v40
	v_mad_u64_u32 v[38:39], s[44:45], v38, s60, v[36:37]
	v_mad_i32_i24 v39, s35, v157, v39
	v_mad_i64_i32 v[34:35], s[44:45], v34, s60, 0
	s_and_b64 vcc, exec, s[6:7]
	s_waitcnt vmcnt(0)
	v_mov_b32_e32 v36, v43
	v_mov_b32_e32 v37, v44
	v_mov_b32_e32 v43, v45
	v_pk_add_f32 v[36:37], v[36:37], v[42:43]
	v_lshl_add_u64 v[42:43], v[38:39], 0, s[8:9]
	v_add_f32_e32 v36, v36, v37
	v_fmamk_f32 v36, v36, 0x3c000000, v155
	v_rsq_f32_e32 v36, v36
	v_lshl_add_u64 v[42:43], v[42:43], 0, v[134:135]
	v_pk_mul_f32 v[30:31], v[30:31], v[36:37] op_sel_hi:[1,0]
	v_pk_mul_f32 v[26:27], v[26:27], v[36:37] op_sel_hi:[1,0]
	v_pk_mul_f32 v[32:33], v[32:33], v[36:37] op_sel_hi:[1,0]
	v_pk_mul_f32 v[28:29], v[28:29], v[36:37] op_sel_hi:[1,0]
	v_cvt_pk_bf16_f32 v30, v30, v31
	v_cvt_pk_bf16_f32 v31, v32, v33
	global_store_dwordx2 v[42:43], v[30:31], off
	v_cvt_pk_bf16_f32 v26, v26, v27
	v_cvt_pk_bf16_f32 v27, v28, v29
	global_store_dwordx2 v[42:43], v[26:27], off offset:32
	s_cbranch_vccnz .LBB0_758
	v_lshlrev_b32_e32 v30, 1, v136
	v_mov_b32_e32 v31, v135
	v_lshl_add_u64 v[30:31], v[38:39], 0, v[30:31]
	global_store_dwordx4 v[30:31], v[230:233], off offset:256
.LBB0_758:
	s_nop 1
	v_or_b32_e32 v28, s42, v40
	v_mov_b64_e32 v[26:27], s[14:15]
	v_mad_u64_u32 v[26:27], s[44:45], v28, s60, v[26:27]
	v_add_u32_e32 v27, s43, v27
	v_mov_b32_e32 v37, v36
	v_lshl_add_u64 v[28:29], v[26:27], 0, s[8:9]
	v_lshl_add_u64 v[28:29], v[28:29], 0, v[134:135]
	v_mov_b32_e32 v30, v36
	v_mov_b32_e32 v31, v36
	v_pk_mul_f32 v[22:23], v[22:23], v[36:37]
	v_pk_mul_f32 v[18:19], v[18:19], v[36:37]
	s_and_b64 vcc, exec, s[6:7]
	v_pk_mul_f32 v[24:25], v[24:25], v[30:31]
	v_cvt_pk_bf16_f32 v22, v22, v23
	v_pk_mul_f32 v[20:21], v[20:21], v[30:31]
	v_cvt_pk_bf16_f32 v23, v24, v25
	global_store_dwordx2 v[28:29], v[22:23], off
	v_cvt_pk_bf16_f32 v18, v18, v19
	v_cvt_pk_bf16_f32 v19, v20, v21
	global_store_dwordx2 v[28:29], v[18:19], off offset:32
	s_cbranch_vccnz .LBB0_760
	v_lshlrev_b32_e32 v22, 1, v136
	v_mov_b32_e32 v23, v135
	v_lshl_add_u64 v[22:23], v[26:27], 0, v[22:23]
	global_store_dwordx4 v[22:23], v[230:233], off offset:256
.LBB0_760:
	s_nop 1
	v_or_b32_e32 v18, 48, v66
	v_ashrrev_i32_e32 v19, 31, v18
	v_lshlrev_b64 v[20:21], 5, v[18:19]
	v_lshl_add_u64 v[20:21], s[10:11], 0, v[20:21]
	global_load_dwordx4 v[26:29], v[20:21], off offset:16
	v_bitop3_b32 v24, v66, s65, 48 bitop3:0xc8
	v_mov_b64_e32 v[20:21], s[14:15]
	v_or_b32_e32 v22, s37, v24
	v_mad_u64_u32 v[22:23], s[44:45], v22, s60, v[20:21]
	v_mad_i32_i24 v23, s35, v157, v23
	v_mad_i64_i32 v[18:19], s[44:45], v18, s60, 0
	s_and_b64 vcc, exec, s[6:7]
	s_waitcnt vmcnt(0)
	v_mov_b32_e32 v20, v27
	v_mov_b32_e32 v21, v28
	v_mov_b32_e32 v27, v29
	v_pk_add_f32 v[20:21], v[20:21], v[26:27]
	v_lshl_add_u64 v[26:27], v[22:23], 0, s[8:9]
	v_add_f32_e32 v20, v20, v21
	v_fmamk_f32 v20, v20, 0x3c000000, v155
	v_rsq_f32_e32 v20, v20
	v_lshl_add_u64 v[26:27], v[26:27], 0, v[134:135]
	v_pk_mul_f32 v[14:15], v[14:15], v[20:21] op_sel_hi:[1,0]
	v_pk_mul_f32 v[10:11], v[10:11], v[20:21] op_sel_hi:[1,0]
	v_pk_mul_f32 v[16:17], v[16:17], v[20:21] op_sel_hi:[1,0]
	v_pk_mul_f32 v[12:13], v[12:13], v[20:21] op_sel_hi:[1,0]
	v_cvt_pk_bf16_f32 v14, v14, v15
	v_cvt_pk_bf16_f32 v15, v16, v17
	global_store_dwordx2 v[26:27], v[14:15], off
	v_cvt_pk_bf16_f32 v10, v10, v11
	v_cvt_pk_bf16_f32 v11, v12, v13
	global_store_dwordx2 v[26:27], v[10:11], off offset:32
	s_cbranch_vccnz .LBB0_762
	v_lshlrev_b32_e32 v14, 1, v136
	v_mov_b32_e32 v15, v135
	v_lshl_add_u64 v[14:15], v[22:23], 0, v[14:15]
	global_store_dwordx4 v[14:15], v[234:237], off offset:256

.LBB0_764:
	v_lshlrev_b32_e32 v6, 1, v136
	v_mov_b32_e32 v7, v135
	v_lshl_add_u64 v[6:7], v[10:11], 0, v[6:7]
	global_store_dwordx4 v[6:7], v[234:237], off offset:256
	s_andn2_b64 vcc, exec, s[4:5]
	s_mov_b64 s[4:5], -1
	s_cbranch_vccnz .LBB0_723
